# v8 plus G1: team 1 forward substitution runs on wave 5 (its own SIMD) instead of wave 4
# speedup vs baseline: 1.0055x; 1.0055x over previous
; DI unsigned pk2(float lo, float hi) { f32x2_t v = {lo, hi}; bf16x2_t b = __builtin_convertvector(v, bf16x2_t); return __builtin_bit_cast(unsigned, b); }
; DI float bflo(unsigned w) { return __uint_as_float(w << 16); }
; DI float bfhi(unsigned w) { return __uint_as_float(w & 0xffff0000u); }
; DI float bf2f(unsigned short b) { return __uint_as_float(((unsigned)b) << 16); }
; DI void g1_team(const Params& p, int j, int unit, lptr lds) {
;     ...
; #pragma unroll
;         for (int half = 0; half < 2; ++half) { const bf16x8 f = pack8(acc, half); const int ksp = 2 * st + half;
;             *(bf16x8*)(qkrec + ((ct * 4 + ksp) * 64 + lane) * 16) = f; }
;     }
;     {
;         const int w2 = lw;
; #pragma unroll
;         for (int q = 0; q < 4; ++q) {
;             const int rt = q & 1, ks = 2 * w2 + (q >> 1); const int c = 32 * rt + r; const float sc = QSCALE * lld<float>(lds, T1_EGC + c * 4);
;             const u32x2 a = lld<u32x2>(lds, T1_Q + c * 272 + (16 * ks + 4 * hh) * 2), bq = lld<u32x2>(lds, T1_Q + c * 272 + (16 * ks + 8 + 4 * hh) * 2);
;             u32x4 o; o.x = pk2(bflo(a.x) * sc, bfhi(a.x) * sc); o.y = pk2(bflo(a.y) * sc, bfhi(a.y) * sc); o.z = pk2(bflo(bq.x) * sc, bfhi(bq.x) * sc); o.w = pk2(bflo(bq.y) * sc, bfhi(bq.y) * sc);
;             *(u32x4*)(rec + 16384 + ((rt * 8 + ks) * 64 + lane) * 16) = o;
;         }
;         const float gl = lld<float>(lds, T1_GC + 63 * 4);
; #pragma unroll
;         for (int ksp = 0; ksp < 4; ++ksp) {
;             float v[8];
; #pragma unroll
;             for (int jx = 0; jx < 8; ++jx) { const int c = krow(ksp, hh, jx); v[jx] = bf2f(lld<unsigned short>(lds, T1_K + c * 272 + (32 * w2 + r) * 2)) * __expf(gl - lld<float>(lds, T1_GC + c * 4)); }
;             u32x4 o; o.x = pk2(v[0], v[1]); o.y = pk2(v[2], v[3]); o.z = pk2(v[4], v[5]); o.w = pk2(v[6], v[7]);
;             *(u32x4*)(rec + 32768 + ((w2 * 4 + ksp) * 64 + lane) * 16) = o;
;         }
;     }
;     __syncthreads();
;     if (lw == 0) {
.LBB0_467:
	s_or_b64 exec, exec, s[2:3]
	s_ashr_i32 s39, s38, 31
	s_lshl_b64 s[2:3], s[38:39], 16
	s_add_u32 s40, s96, s2
	s_addc_u32 s41, s97, s3
	s_lshl_b64 s[2:3], s[38:39], 13
	v_readlane_b32 s12, v252, 8
	s_add_u32 s2, s12, s2
	v_readlane_b32 s12, v252, 9
	s_addc_u32 s3, s12, s3
	s_lshl_b32 s11, s11, 10
	s_lshl_b32 s10, s10, 12
	s_and_b32 s11, s11, 0x800
	v_lshlrev_b32_e32 v6, 4, v135
	s_or_b32 s10, s10, s11
	v_cvt_pk_bf16_f32 v16, v19, v2
	v_cvt_pk_bf16_f32 v17, v18, v4
	v_cvt_pk_bf16_f32 v18, v3, v21
	v_cvt_pk_bf16_f32 v19, v5, v8
	v_or_b32_e32 v8, s10, v6
	v_cvt_pk_bf16_f32 v2, v7, v10
	v_cvt_pk_bf16_f32 v3, v9, v12
	v_cvt_pk_bf16_f32 v4, v11, v14
	v_cvt_pk_bf16_f32 v5, v13, v15
	v_lshl_add_u32 v7, v82, 2, s26
	global_store_dwordx4 v8, v[2:5], s[2:3] offset:1024
	s_lshl_b32 s10, s42, 1
	global_store_dwordx4 v8, v[16:19], s[2:3]
	v_add_u32_e32 v2, 0x11200, v7
	ds_read_b32 v2, v2
	s_add_u32 s2, s40, 0x4000
	v_lshlrev_b32_e32 v87, 3, v0
	s_addc_u32 s3, s41, 0
	v_mov_b32_e32 v0, s26
	s_lshl_b32 s43, s42, 6
	s_movk_i32 s11, 0x110
	v_or_b32_e32 v9, s43, v87
	v_mad_u32_u24 v88, v82, s11, v0
	v_add_u32_e32 v0, v88, v9
	s_waitcnt lgkmcnt(0)
	v_mul_f32_e32 v8, 0x3db504f3, v2
	ds_read2_b64 v[2:5], v0 offset1:2
	v_lshl_or_b32 v0, s42, 11, v6
	v_add_u32_e32 v89, 0x2200, v88
	s_movk_i32 s11, 0x2000
	s_or_b32 s10, s10, 1
	s_waitcnt lgkmcnt(0)
	v_lshlrev_b32_e32 v10, 16, v2
	v_and_b32_e32 v11, 0xffff0000, v2
	v_pk_mul_f32 v[10:11], v[8:9], v[10:11] op_sel_hi:[0,1]
	v_cvt_pk_bf16_f32 v2, v10, v11
	v_lshlrev_b32_e32 v10, 16, v3
	v_and_b32_e32 v11, 0xffff0000, v3
	v_pk_mul_f32 v[10:11], v[8:9], v[10:11] op_sel_hi:[0,1]
	v_cvt_pk_bf16_f32 v3, v10, v11
	v_lshlrev_b32_e32 v10, 16, v4
	v_and_b32_e32 v11, 0xffff0000, v4
	v_pk_mul_f32 v[10:11], v[8:9], v[10:11] op_sel_hi:[0,1]
	v_cvt_pk_bf16_f32 v4, v10, v11
	v_lshlrev_b32_e32 v10, 16, v5
	v_and_b32_e32 v11, 0xffff0000, v5
	v_pk_mul_f32 v[10:11], v[8:9], v[10:11] op_sel_hi:[0,1]
	v_cvt_pk_bf16_f32 v5, v10, v11
	global_store_dwordx4 v0, v[2:5], s[2:3]
	v_lshl_add_u64 v[10:11], s[2:3], 0, v[0:1]
	v_add_co_u32_e32 v10, vcc, s11, v10
	v_add_u32_e32 v2, 0x11280, v7
	ds_read_b32 v2, v2
	s_lshl_b32 s82, s10, 5
	v_addc_co_u32_e32 v11, vcc, 0, v11, vcc
	v_or_b32_e32 v7, s82, v87
	s_waitcnt lgkmcnt(0)
	v_mul_f32_e32 v12, 0x3db504f3, v2
	v_add_u32_e32 v2, v89, v9
	ds_read2_b64 v[2:5], v2 offset1:2
	v_lshl_or_b32 v78, s10, 10, v6
	v_mov_b32_e32 v79, v1
	v_mul_i32_i24_e32 v90, 0x110, v50
	v_lshlrev_b32_e32 v74, 2, v135
	s_waitcnt lgkmcnt(0)
	v_lshlrev_b32_e32 v14, 16, v2
	v_and_b32_e32 v15, 0xffff0000, v2
	v_pk_mul_f32 v[14:15], v[12:13], v[14:15] op_sel_hi:[0,1]
	v_cvt_pk_bf16_f32 v2, v14, v15
	v_lshlrev_b32_e32 v14, 16, v3
	v_and_b32_e32 v15, 0xffff0000, v3
	v_pk_mul_f32 v[14:15], v[12:13], v[14:15] op_sel_hi:[0,1]
	v_cvt_pk_bf16_f32 v3, v14, v15
	v_lshlrev_b32_e32 v14, 16, v4
	v_and_b32_e32 v15, 0xffff0000, v4
	v_pk_mul_f32 v[14:15], v[12:13], v[14:15] op_sel_hi:[0,1]
	v_cvt_pk_bf16_f32 v4, v14, v15
	v_lshlrev_b32_e32 v14, 16, v5
	v_and_b32_e32 v15, 0xffff0000, v5
	v_pk_mul_f32 v[14:15], v[12:13], v[14:15] op_sel_hi:[0,1]
	v_cvt_pk_bf16_f32 v5, v14, v15
	global_store_dwordx4 v[10:11], v[2:5], off
	s_nop 1
	v_add_u32_e32 v2, v88, v7
	ds_read2_b64 v[2:5], v2 offset1:2
	s_waitcnt lgkmcnt(0)
	v_lshlrev_b32_e32 v10, 16, v2
	v_and_b32_e32 v11, 0xffff0000, v2
	v_pk_mul_f32 v[10:11], v[8:9], v[10:11] op_sel_hi:[0,1]
	v_cvt_pk_bf16_f32 v2, v10, v11
	v_lshlrev_b32_e32 v10, 16, v3
	v_and_b32_e32 v11, 0xffff0000, v3
	v_pk_mul_f32 v[10:11], v[8:9], v[10:11] op_sel_hi:[0,1]
	v_cvt_pk_bf16_f32 v3, v10, v11
	v_lshlrev_b32_e32 v10, 16, v4
	v_and_b32_e32 v11, 0xffff0000, v4
	v_pk_mul_f32 v[10:11], v[8:9], v[10:11] op_sel_hi:[0,1]
	v_cvt_pk_bf16_f32 v4, v10, v11
	v_lshlrev_b32_e32 v10, 16, v5
	v_and_b32_e32 v11, 0xffff0000, v5
	v_pk_mul_f32 v[8:9], v[8:9], v[10:11] op_sel_hi:[0,1]
	v_cvt_pk_bf16_f32 v5, v8, v9
	global_store_dwordx4 v78, v[2:5], s[2:3]
	v_lshl_add_u64 v[8:9], s[2:3], 0, v[78:79]
	v_add_co_u32_e32 v8, vcc, s11, v8
	v_add_u32_e32 v2, v89, v7
	ds_read2_b64 v[2:5], v2 offset1:2
	v_addc_co_u32_e32 v9, vcc, 0, v9, vcc
	s_add_i32 s2, s43, s26
	s_mov_b64 s[10:11], 0x8000
	s_waitcnt lgkmcnt(0)
	v_lshlrev_b32_e32 v10, 16, v2
	v_and_b32_e32 v11, 0xffff0000, v2
	v_pk_mul_f32 v[10:11], v[12:13], v[10:11] op_sel_hi:[0,1]
	v_cvt_pk_bf16_f32 v2, v10, v11
	v_lshlrev_b32_e32 v10, 16, v3
	v_and_b32_e32 v11, 0xffff0000, v3
	v_pk_mul_f32 v[10:11], v[12:13], v[10:11] op_sel_hi:[0,1]
	v_cvt_pk_bf16_f32 v3, v10, v11
	v_lshlrev_b32_e32 v10, 16, v4
	v_and_b32_e32 v11, 0xffff0000, v4
	v_pk_mul_f32 v[10:11], v[12:13], v[10:11] op_sel_hi:[0,1]
	v_cvt_pk_bf16_f32 v4, v10, v11
	v_lshlrev_b32_e32 v10, 16, v5
	v_and_b32_e32 v11, 0xffff0000, v5
	v_pk_mul_f32 v[10:11], v[12:13], v[10:11] op_sel_hi:[0,1]
	v_cvt_pk_bf16_f32 v5, v10, v11
	global_store_dwordx4 v[8:9], v[2:5], off
	v_lshlrev_b32_e32 v9, 1, v82
	v_add3_u32 v7, v90, s2, v9
	v_mov_b32_e32 v2, s44
	ds_read_b32 v8, v2
	v_lshl_add_u32 v2, v50, 2, s26
	v_add_u32_e32 v2, 0x11000, v2
	ds_read_b128 v[2:5], v2
	ds_read_u16 v10, v7 offset:17408
	ds_read_u16 v11, v7 offset:17680
	s_mov_b32 s3, 0x8000
	s_cmp_lg_u32 s26, 0
	s_cselect_b32 vcc_lo, 1, 0
	s_cmp_eq_u32 s42, vcc_lo
	s_waitcnt lgkmcnt(2)
	v_sub_f32_e32 v2, v8, v2
	v_sub_f32_e32 v3, v8, v3
	v_mul_f32_e32 v2, 0x3fb8aa3b, v2
	v_mul_f32_e32 v3, 0x3fb8aa3b, v3
	v_exp_f32_e32 v2, v2
	v_exp_f32_e32 v3, v3
	s_waitcnt lgkmcnt(0)
	v_lshlrev_b32_e32 v11, 16, v11
	v_lshlrev_b32_e32 v10, 16, v10
	v_sub_f32_e32 v4, v8, v4
	v_pk_mul_f32 v[2:3], v[2:3], v[10:11]
	ds_read_u16 v10, v7 offset:17952
	ds_read_u16 v7, v7 offset:18224
	v_sub_f32_e32 v5, v8, v5
	v_mul_f32_e32 v4, 0x3fb8aa3b, v4
	v_mul_f32_e32 v5, 0x3fb8aa3b, v5
	v_exp_f32_e32 v4, v4
	s_waitcnt lgkmcnt(0)
; DI unsigned pk2(float lo, float hi) { f32x2_t v = {lo, hi}; bf16x2_t b = __builtin_convertvector(v, bf16x2_t); return __builtin_bit_cast(unsigned, b); }
; DI float bf2f(unsigned short b) { return __uint_as_float(((unsigned)b) << 16); }
; DI void g1_team(const Params& p, int j, int unit, lptr lds) {
;     ...
;         const float gl = lld<float>(lds, T1_GC + 63 * 4);
; #pragma unroll
;         for (int ksp = 0; ksp < 4; ++ksp) {
;             float v[8];
; #pragma unroll
;             for (int jx = 0; jx < 8; ++jx) { const int c = krow(ksp, hh, jx); v[jx] = bf2f(lld<unsigned short>(lds, T1_K + c * 272 + (32 * w2 + r) * 2)) * __expf(gl - lld<float>(lds, T1_GC + c * 4)); }
;             u32x4 o; o.x = pk2(v[0], v[1]); o.y = pk2(v[2], v[3]); o.z = pk2(v[4], v[5]); o.w = pk2(v[6], v[7]);
;             *(u32x4*)(rec + 32768 + ((w2 * 4 + ksp) * 64 + lane) * 16) = o;
;         }
	v_lshlrev_b32_e32 v11, 16, v7
	v_or_b32_e32 v7, 8, v50
	v_mul_i32_i24_e32 v91, 0x110, v7
	v_lshl_add_u32 v7, v7, 2, s26
	v_add_u32_e32 v7, 0x11000, v7
	ds_read_b32 v7, v7
	v_exp_f32_e32 v5, v5
	v_lshlrev_b32_e32 v10, 16, v10
	v_add3_u32 v12, s2, v91, v9
	s_waitcnt lgkmcnt(0)
	v_sub_f32_e32 v7, v8, v7
	v_mul_f32_e32 v7, 0x3fb8aa3b, v7
	v_pk_mul_f32 v[4:5], v[4:5], v[10:11]
	v_exp_f32_e32 v10, v7
	v_or_b32_e32 v7, 9, v50
	v_mul_i32_i24_e32 v11, 0x110, v7
	v_lshl_add_u32 v7, v7, 2, s26
	v_add_u32_e32 v7, 0x11000, v7
	ds_read_b32 v7, v7
	v_add3_u32 v13, s2, v11, v9
	s_waitcnt lgkmcnt(0)
	v_sub_f32_e32 v7, v8, v7
	v_mul_f32_e32 v7, 0x3fb8aa3b, v7
	v_exp_f32_e32 v11, v7
	ds_read_u16 v7, v12 offset:17408
	ds_read_u16 v12, v13 offset:17408
	s_waitcnt lgkmcnt(0)
	v_lshlrev_b32_e32 v13, 16, v12
	v_lshlrev_b32_e32 v12, 16, v7
	v_or_b32_e32 v7, 10, v50
	v_pk_mul_f32 v[12:13], v[10:11], v[12:13]
	v_mul_i32_i24_e32 v10, 0x110, v7
	v_lshl_add_u32 v7, v7, 2, s26
	v_add_u32_e32 v7, 0x11000, v7
	ds_read_b32 v7, v7
	v_add3_u32 v14, s2, v10, v9
	v_cvt_pk_bf16_f32 v12, v12, v13
	s_waitcnt lgkmcnt(0)
	v_sub_f32_e32 v7, v8, v7
	v_mul_f32_e32 v7, 0x3fb8aa3b, v7
	v_exp_f32_e32 v10, v7
	v_or_b32_e32 v7, 11, v50
	v_mul_i32_i24_e32 v11, 0x110, v7
	v_lshl_add_u32 v7, v7, 2, s26
	v_add_u32_e32 v7, 0x11000, v7
	ds_read_b32 v7, v7
	v_add3_u32 v15, s2, v11, v9
	s_waitcnt lgkmcnt(0)
	v_sub_f32_e32 v7, v8, v7
	v_mul_f32_e32 v7, 0x3fb8aa3b, v7
	v_exp_f32_e32 v11, v7
	ds_read_u16 v7, v14 offset:17408
	ds_read_u16 v14, v15 offset:17408
	s_waitcnt lgkmcnt(0)
	v_lshlrev_b32_e32 v15, 16, v14
	v_lshlrev_b32_e32 v14, 16, v7
	v_pk_mul_f32 v[14:15], v[10:11], v[14:15]
	v_cvt_pk_bf16_f32 v10, v2, v3
	v_lshl_or_b32 v2, s42, 12, v6
	v_mov_b32_e32 v3, v1
	v_cvt_pk_bf16_f32 v11, v4, v5
	v_lshl_add_u64 v[4:5], s[40:41], 0, v[2:3]
	v_lshl_add_u64 v[2:3], v[4:5], 0, s[10:11]
	v_add_co_u32_e32 v4, vcc, s3, v4
	v_cvt_pk_bf16_f32 v13, v14, v15
	s_nop 0
	v_addc_co_u32_e32 v5, vcc, 0, v5, vcc
	global_store_dwordx4 v[4:5], v[10:13], off
	v_or_b32_e32 v4, 16, v50
	v_or_b32_e32 v5, 17, v50
	v_mul_i32_i24_e32 v92, 0x110, v4
	v_lshl_add_u32 v4, v4, 2, s26
	v_mul_i32_i24_e32 v7, 0x110, v5
	v_lshl_add_u32 v5, v5, 2, s26
	v_add_u32_e32 v4, 0x11000, v4
	v_add_u32_e32 v5, 0x11000, v5
	ds_read_b32 v4, v4
	ds_read_b32 v5, v5
	v_add3_u32 v6, s2, v92, v9
	v_add3_u32 v7, s2, v7, v9
	ds_read_u16 v6, v6 offset:17408
	ds_read_u16 v7, v7 offset:17408
	s_waitcnt lgkmcnt(3)
	v_sub_f32_e32 v4, v8, v4
	s_waitcnt lgkmcnt(2)
	v_sub_f32_e32 v5, v8, v5
	v_mul_f32_e32 v4, 0x3fb8aa3b, v4
	v_mul_f32_e32 v5, 0x3fb8aa3b, v5
	v_exp_f32_e32 v4, v4
	v_exp_f32_e32 v5, v5
	s_waitcnt lgkmcnt(0)
	v_lshlrev_b32_e32 v7, 16, v7
	v_lshlrev_b32_e32 v6, 16, v6
	v_pk_mul_f32 v[4:5], v[4:5], v[6:7]
	v_or_b32_e32 v6, 18, v50
	v_mul_i32_i24_e32 v7, 0x110, v6
	v_add3_u32 v10, s2, v7, v9
	v_or_b32_e32 v7, 19, v50
	v_lshl_add_u32 v6, v6, 2, s26
	v_mul_i32_i24_e32 v11, 0x110, v7
	v_lshl_add_u32 v7, v7, 2, s26
	v_add_u32_e32 v6, 0x11000, v6
	v_add_u32_e32 v7, 0x11000, v7
	ds_read_b32 v6, v6
	ds_read_b32 v7, v7
	v_add3_u32 v11, s2, v11, v9
	ds_read_u16 v10, v10 offset:17408
	ds_read_u16 v11, v11 offset:17408
	v_cvt_pk_bf16_f32 v4, v4, v5
	s_waitcnt lgkmcnt(3)
	v_sub_f32_e32 v6, v8, v6
	s_waitcnt lgkmcnt(2)
	v_sub_f32_e32 v7, v8, v7
	v_mul_f32_e32 v6, 0x3fb8aa3b, v6
	v_mul_f32_e32 v7, 0x3fb8aa3b, v7
	v_exp_f32_e32 v6, v6
	v_exp_f32_e32 v7, v7
	s_waitcnt lgkmcnt(0)
	v_lshlrev_b32_e32 v11, 16, v11
	v_lshlrev_b32_e32 v10, 16, v10
	v_pk_mul_f32 v[6:7], v[6:7], v[10:11]
	v_or_b32_e32 v10, 24, v50
	v_mul_i32_i24_e32 v11, 0x110, v10
	v_add3_u32 v12, s2, v11, v9
	v_or_b32_e32 v11, 25, v50
	v_lshl_add_u32 v10, v10, 2, s26
	v_mul_i32_i24_e32 v13, 0x110, v11
	v_lshl_add_u32 v11, v11, 2, s26
	v_add_u32_e32 v10, 0x11000, v10
	v_add_u32_e32 v11, 0x11000, v11
	ds_read_b32 v10, v10
	ds_read_b32 v11, v11
	v_add3_u32 v13, s2, v13, v9
	ds_read_u16 v12, v12 offset:17408
	ds_read_u16 v13, v13 offset:17408
	v_cvt_pk_bf16_f32 v5, v6, v7
	s_waitcnt lgkmcnt(3)
	v_sub_f32_e32 v10, v8, v10
	s_waitcnt lgkmcnt(2)
	v_sub_f32_e32 v11, v8, v11
	v_mul_f32_e32 v10, 0x3fb8aa3b, v10
	v_mul_f32_e32 v11, 0x3fb8aa3b, v11
	v_exp_f32_e32 v10, v10
	v_exp_f32_e32 v11, v11
	s_waitcnt lgkmcnt(0)
	v_lshlrev_b32_e32 v13, 16, v13
	v_lshlrev_b32_e32 v12, 16, v12
	v_pk_mul_f32 v[10:11], v[10:11], v[12:13]
	v_or_b32_e32 v12, 26, v50
	v_mul_i32_i24_e32 v13, 0x110, v12
	v_add3_u32 v14, s2, v13, v9
	v_or_b32_e32 v13, 27, v50
	v_lshl_add_u32 v12, v12, 2, s26
	v_mul_i32_i24_e32 v15, 0x110, v13
	v_lshl_add_u32 v13, v13, 2, s26
	v_add_u32_e32 v12, 0x11000, v12
	v_add_u32_e32 v13, 0x11000, v13
	ds_read_b32 v12, v12
	ds_read_b32 v13, v13
	v_add3_u32 v15, s2, v15, v9
	ds_read_u16 v14, v14 offset:17408
	ds_read_u16 v15, v15 offset:17408
	v_cvt_pk_bf16_f32 v6, v10, v11
	s_waitcnt lgkmcnt(3)
	v_sub_f32_e32 v12, v8, v12
	s_waitcnt lgkmcnt(2)
	v_sub_f32_e32 v13, v8, v13
	v_mul_f32_e32 v12, 0x3fb8aa3b, v12
	v_mul_f32_e32 v13, 0x3fb8aa3b, v13
	v_exp_f32_e32 v12, v12
	v_exp_f32_e32 v13, v13
	s_waitcnt lgkmcnt(0)
	v_lshlrev_b32_e32 v15, 16, v15
	v_lshlrev_b32_e32 v14, 16, v14
	v_pk_mul_f32 v[12:13], v[12:13], v[14:15]
	s_nop 0
	v_cvt_pk_bf16_f32 v7, v12, v13
	global_store_dwordx4 v[2:3], v[4:7], off offset:1024
	s_nop 1
	v_or_b32_e32 v4, 32, v50
	v_or_b32_e32 v5, 33, v50
	v_mul_i32_i24_e32 v93, 0x110, v4
	v_lshl_add_u32 v4, v4, 2, s26
	v_mul_i32_i24_e32 v94, 0x110, v5
	v_lshl_add_u32 v5, v5, 2, s26
	v_add_u32_e32 v4, 0x11000, v4
	v_add_u32_e32 v5, 0x11000, v5
	ds_read_b32 v4, v4
	ds_read_b32 v5, v5
	v_add3_u32 v6, s2, v93, v9
	v_add3_u32 v7, s2, v94, v9
	ds_read_u16 v6, v6 offset:17408
	ds_read_u16 v7, v7 offset:17408
	s_waitcnt lgkmcnt(3)
; DI unsigned pk2(float lo, float hi) { f32x2_t v = {lo, hi}; bf16x2_t b = __builtin_convertvector(v, bf16x2_t); return __builtin_bit_cast(unsigned, b); }
; DI float bf2f(unsigned short b) { return __uint_as_float(((unsigned)b) << 16); }
; DI void g1_team(const Params& p, int j, int unit, lptr lds) {
;     ...
;         for (int ksp = 0; ksp < 4; ++ksp) {
;             float v[8];
; #pragma unroll
;             for (int jx = 0; jx < 8; ++jx) { const int c = krow(ksp, hh, jx); v[jx] = bf2f(lld<unsigned short>(lds, T1_K + c * 272 + (32 * w2 + r) * 2)) * __expf(gl - lld<float>(lds, T1_GC + c * 4)); }
;             u32x4 o; o.x = pk2(v[0], v[1]); o.y = pk2(v[2], v[3]); o.z = pk2(v[4], v[5]); o.w = pk2(v[6], v[7]);
;             *(u32x4*)(rec + 32768 + ((w2 * 4 + ksp) * 64 + lane) * 16) = o;
;         }
;     }
;     __syncthreads();
;     if (lw == 0) {
	v_sub_f32_e32 v4, v8, v4
	s_waitcnt lgkmcnt(2)
	v_sub_f32_e32 v5, v8, v5
	v_mul_f32_e32 v4, 0x3fb8aa3b, v4
	v_mul_f32_e32 v5, 0x3fb8aa3b, v5
	v_exp_f32_e32 v4, v4
	v_exp_f32_e32 v5, v5
	s_waitcnt lgkmcnt(0)
	v_lshlrev_b32_e32 v7, 16, v7
	v_lshlrev_b32_e32 v6, 16, v6
	v_pk_mul_f32 v[4:5], v[4:5], v[6:7]
	v_or_b32_e32 v6, 34, v50
	v_or_b32_e32 v7, 35, v50
	v_mul_i32_i24_e32 v95, 0x110, v6
	v_lshl_add_u32 v6, v6, 2, s26
	v_mul_i32_i24_e32 v96, 0x110, v7
	v_lshl_add_u32 v7, v7, 2, s26
	v_add_u32_e32 v6, 0x11000, v6
	v_add_u32_e32 v7, 0x11000, v7
	ds_read_b32 v6, v6
	ds_read_b32 v7, v7
	v_add3_u32 v10, s2, v95, v9
	v_add3_u32 v11, s2, v96, v9
	ds_read_u16 v10, v10 offset:17408
	ds_read_u16 v11, v11 offset:17408
	s_waitcnt lgkmcnt(3)
	v_sub_f32_e32 v6, v8, v6
	s_waitcnt lgkmcnt(2)
	v_sub_f32_e32 v7, v8, v7
	v_mul_f32_e32 v6, 0x3fb8aa3b, v6
	v_mul_f32_e32 v7, 0x3fb8aa3b, v7
	v_exp_f32_e32 v6, v6
	v_exp_f32_e32 v7, v7
	s_waitcnt lgkmcnt(0)
	v_lshlrev_b32_e32 v11, 16, v11
	v_lshlrev_b32_e32 v10, 16, v10
	v_cvt_pk_bf16_f32 v4, v4, v5
	v_pk_mul_f32 v[6:7], v[6:7], v[10:11]
	v_or_b32_e32 v10, 40, v50
	v_or_b32_e32 v11, 41, v50
	v_mul_i32_i24_e32 v97, 0x110, v10
	v_lshl_add_u32 v10, v10, 2, s26
	v_mul_i32_i24_e32 v98, 0x110, v11
	v_lshl_add_u32 v11, v11, 2, s26
	v_add_u32_e32 v10, 0x11000, v10
	v_add_u32_e32 v11, 0x11000, v11
	ds_read_b32 v10, v10
	ds_read_b32 v11, v11
	v_add3_u32 v12, s2, v97, v9
	v_add3_u32 v13, s2, v98, v9
	ds_read_u16 v12, v12 offset:17408
	ds_read_u16 v13, v13 offset:17408
	s_waitcnt lgkmcnt(3)
	v_sub_f32_e32 v10, v8, v10
	s_waitcnt lgkmcnt(2)
	v_sub_f32_e32 v11, v8, v11
	v_mul_f32_e32 v10, 0x3fb8aa3b, v10
	v_mul_f32_e32 v11, 0x3fb8aa3b, v11
	v_exp_f32_e32 v10, v10
	v_exp_f32_e32 v11, v11
	s_waitcnt lgkmcnt(0)
	v_lshlrev_b32_e32 v13, 16, v13
	v_lshlrev_b32_e32 v12, 16, v12
	v_cvt_pk_bf16_f32 v5, v6, v7
	v_pk_mul_f32 v[10:11], v[10:11], v[12:13]
	v_or_b32_e32 v12, 42, v50
	v_or_b32_e32 v13, 43, v50
	v_mul_i32_i24_e32 v99, 0x110, v12
	v_lshl_add_u32 v12, v12, 2, s26
	v_mul_i32_i24_e32 v100, 0x110, v13
	v_lshl_add_u32 v13, v13, 2, s26
	v_add_u32_e32 v12, 0x11000, v12
	v_add_u32_e32 v13, 0x11000, v13
	ds_read_b32 v12, v12
	ds_read_b32 v13, v13
	v_add3_u32 v14, s2, v99, v9
	v_add3_u32 v15, s2, v100, v9
	ds_read_u16 v14, v14 offset:17408
	ds_read_u16 v15, v15 offset:17408
	s_waitcnt lgkmcnt(3)
	v_sub_f32_e32 v12, v8, v12
	s_waitcnt lgkmcnt(2)
	v_sub_f32_e32 v13, v8, v13
	v_mul_f32_e32 v12, 0x3fb8aa3b, v12
	v_mul_f32_e32 v13, 0x3fb8aa3b, v13
	v_exp_f32_e32 v12, v12
	v_exp_f32_e32 v13, v13
	s_waitcnt lgkmcnt(0)
	v_lshlrev_b32_e32 v15, 16, v15
	v_lshlrev_b32_e32 v14, 16, v14
	v_cvt_pk_bf16_f32 v6, v10, v11
	v_pk_mul_f32 v[12:13], v[12:13], v[14:15]
	s_nop 0
	v_cvt_pk_bf16_f32 v7, v12, v13
	global_store_dwordx4 v[2:3], v[4:7], off offset:2048
	s_nop 1
	v_or_b32_e32 v4, 48, v50
	v_or_b32_e32 v5, 49, v50
	v_mul_i32_i24_e32 v101, 0x110, v4
	v_lshl_add_u32 v4, v4, 2, s26
	v_mul_i32_i24_e32 v102, 0x110, v5
	v_lshl_add_u32 v5, v5, 2, s26
	v_add_u32_e32 v4, 0x11000, v4
	v_add_u32_e32 v5, 0x11000, v5
	ds_read_b32 v4, v4
	ds_read_b32 v5, v5
	v_add3_u32 v6, s2, v101, v9
	v_add3_u32 v7, s2, v102, v9
	ds_read_u16 v6, v6 offset:17408
	ds_read_u16 v7, v7 offset:17408
	s_waitcnt lgkmcnt(3)
	v_sub_f32_e32 v4, v8, v4
	s_waitcnt lgkmcnt(2)
	v_sub_f32_e32 v5, v8, v5
	v_mul_f32_e32 v4, 0x3fb8aa3b, v4
	v_mul_f32_e32 v5, 0x3fb8aa3b, v5
	v_exp_f32_e32 v4, v4
	v_exp_f32_e32 v5, v5
	s_waitcnt lgkmcnt(0)
	v_lshlrev_b32_e32 v7, 16, v7
	v_lshlrev_b32_e32 v6, 16, v6
	v_pk_mul_f32 v[4:5], v[4:5], v[6:7]
	v_or_b32_e32 v6, 50, v50
	v_or_b32_e32 v7, 51, v50
	v_mul_i32_i24_e32 v103, 0x110, v6
	v_lshl_add_u32 v6, v6, 2, s26
	v_mul_i32_i24_e32 v104, 0x110, v7
	v_lshl_add_u32 v7, v7, 2, s26
	v_add_u32_e32 v6, 0x11000, v6
	v_add_u32_e32 v7, 0x11000, v7
	ds_read_b32 v6, v6
	ds_read_b32 v7, v7
	v_add3_u32 v10, s2, v103, v9
	v_add3_u32 v11, s2, v104, v9
	ds_read_u16 v10, v10 offset:17408
	ds_read_u16 v11, v11 offset:17408
	s_waitcnt lgkmcnt(3)
	v_sub_f32_e32 v6, v8, v6
	s_waitcnt lgkmcnt(2)
	v_sub_f32_e32 v7, v8, v7
	v_mul_f32_e32 v6, 0x3fb8aa3b, v6
	v_mul_f32_e32 v7, 0x3fb8aa3b, v7
	v_exp_f32_e32 v6, v6
	v_exp_f32_e32 v7, v7
	s_waitcnt lgkmcnt(0)
	v_lshlrev_b32_e32 v11, 16, v11
	v_lshlrev_b32_e32 v10, 16, v10
	v_cvt_pk_bf16_f32 v4, v4, v5
	v_pk_mul_f32 v[6:7], v[6:7], v[10:11]
	v_or_b32_e32 v10, 56, v50
	v_or_b32_e32 v11, 57, v50
	v_mul_i32_i24_e32 v105, 0x110, v10
	v_lshl_add_u32 v10, v10, 2, s26
	v_mul_i32_i24_e32 v106, 0x110, v11
	v_lshl_add_u32 v11, v11, 2, s26
	v_add_u32_e32 v10, 0x11000, v10
	v_add_u32_e32 v11, 0x11000, v11
	ds_read_b32 v10, v10
	ds_read_b32 v11, v11
	v_add3_u32 v12, s2, v105, v9
	v_add3_u32 v13, s2, v106, v9
	ds_read_u16 v12, v12 offset:17408
	ds_read_u16 v13, v13 offset:17408
	s_waitcnt lgkmcnt(3)
	v_sub_f32_e32 v10, v8, v10
	s_waitcnt lgkmcnt(2)
	v_sub_f32_e32 v11, v8, v11
	v_mul_f32_e32 v10, 0x3fb8aa3b, v10
	v_mul_f32_e32 v11, 0x3fb8aa3b, v11
	v_exp_f32_e32 v10, v10
	v_exp_f32_e32 v11, v11
	s_waitcnt lgkmcnt(0)
	v_lshlrev_b32_e32 v13, 16, v13
	v_lshlrev_b32_e32 v12, 16, v12
	v_cvt_pk_bf16_f32 v5, v6, v7
	v_pk_mul_f32 v[10:11], v[10:11], v[12:13]
	v_or_b32_e32 v12, 58, v50
	v_or_b32_e32 v13, 59, v50
	v_mul_i32_i24_e32 v107, 0x110, v12
	v_lshl_add_u32 v12, v12, 2, s26
	v_mul_i32_i24_e32 v108, 0x110, v13
	v_lshl_add_u32 v13, v13, 2, s26
	v_add_u32_e32 v12, 0x11000, v12
	v_add_u32_e32 v13, 0x11000, v13
	ds_read_b32 v12, v12
	ds_read_b32 v13, v13
	v_add3_u32 v14, s2, v107, v9
	v_add3_u32 v9, s2, v108, v9
	v_cvt_pk_bf16_f32 v6, v10, v11
	s_waitcnt lgkmcnt(1)
	v_sub_f32_e32 v12, v8, v12
	s_waitcnt lgkmcnt(0)
	v_sub_f32_e32 v8, v8, v13
	v_mul_f32_e32 v8, 0x3fb8aa3b, v8
	v_exp_f32_e32 v13, v8
	ds_read_u16 v8, v14 offset:17408
	ds_read_u16 v9, v9 offset:17408
	v_mul_f32_e32 v12, 0x3fb8aa3b, v12
	v_exp_f32_e32 v12, v12
	s_waitcnt lgkmcnt(1)
	v_lshlrev_b32_e32 v8, 16, v8
	s_waitcnt lgkmcnt(0)
	v_lshlrev_b32_e32 v9, 16, v9
	v_pk_mul_f32 v[8:9], v[12:13], v[8:9]
	s_nop 0
	v_cvt_pk_bf16_f32 v7, v8, v9
	global_store_dwordx4 v[2:3], v[4:7], off offset:3072
	s_barrier
	s_cbranch_scc1 .LBB0_472
	v_lshlrev_b32_e32 v2, 2, v135
	s_cbranch_execnz .LBB0_470
